# opt26: opt19 + diff-attention loop: tile sa+2's four LDS-DMA pieces issued between tile a's P.V and tile b's softmax instead of at the loop head
# speedup vs baseline: 1.0224x; 1.0085x over previous
; #define DMA_T(s_) do { DMA_K(s_); DMA_V(s_); } while (0)
; #define CLASSIFY(kv0_, act_, cls_) do { act_ = true; if (SWA) act_ = ((kv0_) + 63 >= qw - 128) && ((kv0_) <= qw + 159); \
;         cls_ = 0; if ((kv0_) + 63 < qw) cls_ = 1; else if ((kv0_) > qw + 31) cls_ = 2; \
;         if (SWA) { if (cls_ == 1 && qw + 31 - (kv0_) > 128) cls_ = 0; if (cls_ == 2 && (kv0_) + 63 - qw > 128) cls_ = 0; } } while (0)
; template <bool SWA>
; __device__ __forceinline__ void unit(LAS unsigned char* lds, const bf16_t* PROJ, const bf16_t* KT, const bf16_t* VT, bf16_t* OB, int opitch, int ocol, int b, int head, int qb, float slope2, float m_init, float lam, const float* subg) {
;     ...
;     for (int S = 0; S < npairs; ++S) {
;         const int sa = 2 * S, sb = 2 * S + 1;
;         if (sa + 2 < nsteps) DMA_T(sa + 2);
;         if (sb + 2 < nsteps) DMA_T(sb + 2);
;         const int kva = TILE_OF(sa) * 64, kvb = TILE_OF(sb < nsteps ? sb : sa) * 64;
;         bool acta, actb; int clsa, clsb;
;         CLASSIFY(kva, acta, clsa); CLASSIFY(kvb, actb, clsb); actb = actb && (sb < nsteps);
;         f32x16 s0, s1, u0, u1;
;         if (acta) QK_T(s0, s1, sa, clsa);
.LBB0_884:
	s_add_i32 s29, s1, -3
	s_add_i32 s27, s1, -2
	s_add_i32 s6, s1, -1
	s_cmp_lt_u32 s29, s0
	s_cselect_b32 s6, s29, s6
	s_mov_b32 s28, s26
	s_lshl_b32 s26, s6, 14
	s_cmp_lt_u32 s27, s0
	s_cselect_b32 s6, s27, s1
	s_lshl_b32 s26, s6, 14
	s_add_u32 s98, s73, s26
	s_addc_u32 s99, s17, 0
	s_add_u32 s100, s2, s26
	s_addc_u32 s101, s23, 0
	s_and_b32 s30, s25, 0xc000
	s_add_i32 s32, s30, s33
	s_add_i32 s71, s30, s72
	s_add_i32 s26, s28, 0x80
	s_cmp_gt_u32 s29, s0
	s_cselect_b64 s[78:79], -1, 0
	s_and_b64 s[6:7], s[78:79], exec
	s_cselect_b32 s30, s26, s28
	s_or_b32 s28, s30, 63
	s_cmp_ge_i32 s28, s5
	s_cselect_b64 s[6:7], -1, 0
	s_cmp_lt_i32 s28, s5
	s_cselect_b64 s[82:83], -1, 0
	s_cmp_le_i32 s30, s19
	s_cselect_b64 s[80:81], -1, 0
	s_and_b64 s[84:85], s[6:7], s[80:81]
	s_and_b64 vcc, exec, s[84:85]
	v_mov_b32_e32 v64, 0
	s_cbranch_vccnz .LBB0_886
	s_and_b64 s[28:29], s[80:81], exec
	s_cselect_b32 s28, 0, 64
	s_and_b64 s[6:7], s[6:7], exec
	s_cselect_b32 s6, s28, 0
	s_add_i32 s6, s6, 0
	s_add_i32 s6, s6, 0x20200
	v_mov_b32_e32 v65, s6
	ds_read_b128 v[96:99], v65
	ds_read_b128 v[100:103], v65 offset:16
	ds_read_b128 v[104:107], v65 offset:32
	ds_read_b128 v[108:111], v65 offset:48
	s_branch .LBB0_887

; template <bool SWA>
; __device__ __forceinline__ void unit(LAS unsigned char* lds, const bf16_t* PROJ, const bf16_t* KT, const bf16_t* VT, bf16_t* OB, int opitch, int ocol, int b, int head, int qb, float slope2, float m_init, float lam, const float* subg) {
;     ...
;         if (acta) { SM_T(s0, s1, kva, clsa); if (pvalid) PV_TILE(sa); }
;         if (actb) { SM_T(u0, u1, kvb, clsb); if (pvalid) PV_TILE(sb); }
.LBB0_903:
	s_add_i32 s29, s1, -3
	s_add_i32 s30, s1, -1
	s_cmp_lt_u32 s29, s0
	s_cselect_b32 s30, s29, s30
	s_lshl_b32 s30, s30, 14
	s_add_i32 s31, s25, 0xffffc000
	s_and_b32 s31, s31, 0x8000
	s_add_u32 s98, s73, s30
	s_addc_u32 s99, s17, 0
	s_add_i32 s92, s31, s33
	s_mov_b32 m0, s92
	s_nop 0
	global_load_lds_dwordx4 v164, s[98:99]
	s_add_i32 m0, s92, 0x400
	s_nop 0
	global_load_lds_dwordx4 v170, s[98:99]
	s_add_u32 s98, s2, s30
	s_addc_u32 s99, s23, 0
	s_add_i32 s92, s31, s72
	s_mov_b32 m0, s92
	s_nop 0
	global_load_lds_dwordx4 v168, s[98:99]
	s_add_i32 m0, s92, 0x400
	s_nop 0
	global_load_lds_dwordx4 v172, s[98:99]
	v_or_b32_e32 v96, s28, v187
	v_sub_u32_e32 v96, v188, v96
	v_cvt_f32_i32_e32 v96, v96
	s_mov_b64 s[6:7], -1
	s_and_b64 vcc, exec, s[80:81]
	s_cbranch_vccz .LBB0_909
	s_andn2_b64 vcc, exec, s[78:79]
	s_cbranch_vccnz .LBB0_906
	v_mul_f32_e64 v97, -s76, v96
	v_fma_f32 v98, -s76, v96, v194
	s_mov_b64 s[6:7], 0
